# P3 weight-copy loop: per-item kernarg pointer s_loads hoisted in front of the loop
# baseline (speedup 1.0000x reference)
; #define LAS __attribute__((address_space(3)))
; __device__ __forceinline__ void tr_item(const float* __restrict__ W, int ldw, int K, bf16* __restrict__ WT, int nblk, int mapmode, const float* __restrict__ ksc, LAS float* scr, int item, int lane) {
;     const int kb = item / nblk, nb = item - kb * nblk, k0 = 64 * kb, n0 = 32 * nb;
;     const int L = (n0 & ~255) + 64 * ((n0 >> 5) & 3) + 32 * ((n0 >> 7) & 1);
;     const int src0 = mapmode ? ((L >> 5) & 1) * DFF + 128 * (L >> 8) + 32 * ((L >> 6) & 3) : L;
;     f32x4 v[8];
; #pragma unroll
;     for (int i = 0; i < 8; ++i) { const int kk = 8 * i + (lane >> 3); v[i] = __builtin_nontemporal_load((const f32x4*)(W + (size_t)(k0 + kk) * ldw + src0 + 4 * (lane & 7))); }
; #pragma unroll
;     for (int i = 0; i < 8; ++i) { const int kk = 8 * i + (lane >> 3); f32x4 w = v[i]; if (ksc) w *= ksc[k0 + kk];
;         LAS float* d = scr + kk * 33 + 4 * (lane & 7); d[0] = w[0]; d[1] = w[1]; d[2] = w[2]; d[3] = w[3]; }
;     asm volatile("s_waitcnt lgkmcnt(0)" ::: "memory");
;     const int c = lane & 7;
; #pragma unroll
;     for (int j = 0; j < 4; ++j) { const int n = (lane >> 3) + 8 * j; const LAS float* s = scr + (8 * c) * 33 + n;
; __global__ void __launch_bounds__(NWAVES * 64, 2) hybrid_fwd(Params P) {
;     ...
;             constexpr int I_GLU = 8 * 16, I_SO = 8 * 32, I_AO = 8 * 32, I_WO = 16 * 32, I_UP = 16 * 176, I_DN = 44 * 32;
;             constexpr int NITEMS = I_GLU + I_SO + I_AO + I_WO + I_UP + I_DN;
;             const int tw0 = nscan == G ? gw : (bx - nscan) * NWAVES + wave, tnw = nscan == G ? NGW : (G - nscan) * NWAVES;
;             for (int it = tw0; it < NITEMS; it += tnw) {
.LBB0_514:
	v_writelane_b32 v240, s84, 6
	s_or_b64 s[6:7], s[4:5], s[6:7]
	s_andn2_b64 vcc, exec, s[6:7]
	v_writelane_b32 v240, s85, 7
	v_writelane_b32 v240, s82, 8
	s_nop 1
	v_writelane_b32 v240, s83, 9
	v_writelane_b32 v240, s80, 10
	s_nop 1
	v_writelane_b32 v240, s81, 11
	s_cbranch_vccnz .LBB0_554
	s_sub_i32 s6, s2, s14
	s_lshl_b32 s6, s6, 3
	v_readlane_b32 s7, v240, 3
	s_add_i32 s8, s6, s7
	s_and_b64 s[6:7], s[4:5], exec
	s_cselect_b32 s28, s57, s8
	s_cmpk_gt_i32 s28, 0x14ff
	s_cbranch_scc1 .LBB0_554
	s_load_dwordx2 s[60:61], s[0:1], 0xe0
	s_load_dwordx2 s[62:63], s[0:1], 0xc8
	s_load_dwordx2 s[64:65], s[0:1], 0xc0
	s_load_dwordx2 s[66:67], s[0:1], 0xb8
	s_load_dwordx2 s[68:69], s[0:1], 0xb0
	s_load_dwordx2 s[70:71], s[0:1], 0xa8
	s_load_dwordx2 s[72:73], s[0:1], 0x60
	s_load_dwordx2 s[74:75], s[0:1], 0xf0
	s_waitcnt lgkmcnt(0)
	s_sub_i32 s6, s3, s14
	s_lshl_b32 s6, s6, 3
	s_and_b64 s[4:5], s[4:5], exec
	v_readlane_b32 s4, v240, 3
	v_lshlrev_b32_e32 v4, 3, v218
	s_cselect_b32 s29, s56, s6
	s_lshl_b32 s4, s4, 14
	v_lshrrev_b32_e32 v1, 3, v174
	v_lshlrev_b32_e32 v2, 2, v218
	v_and_b32_e32 v4, 56, v4
	s_add_i32 s4, s4, 0
	v_and_b32_e32 v2, 28, v2
	v_mul_u32_u24_e32 v6, 0x84, v4
	v_lshlrev_b32_e32 v7, 2, v1
	v_lshl_add_u32 v3, v2, 2, s4
	v_mul_u32_u24_e32 v5, 0x84, v1
	v_add3_u32 v49, s4, v6, v7
	v_or_b32_e32 v6, 32, v1
	v_mul_u32_u24_e32 v6, 0x84, v6
	s_lshl_b32 s30, s28, 5
	s_lshl_b32 s4, s28, 4
	v_add_u32_e32 v51, v3, v5
	s_mov_b32 s7, 0
	v_mov_b32_e32 v39, 0
	v_or_b32_e32 v46, 8, v1
	v_or_b32_e32 v47, 16, v1
	v_or_b32_e32 v48, 24, v1
	s_lshl_b32 s31, s29, 5
	s_lshl_b32 s33, s28, 3
	s_lshl_b32 s34, s29, 3
	s_lshl_b32 s35, s28, 6
	s_lshl_b32 s36, s29, 6
	s_lshl_b32 s37, s28, 1
	s_lshl_b32 s40, s29, 1
	s_add_i32 s41, s28, 0xfb80
	s_add_i32 s42, s4, 0xffffb800
	s_lshl_b32 s43, s29, 4
	v_or_b32_e32 v50, s30, v1
	s_mov_b32 s44, 0x8000
	s_mov_b32 s45, 0x10000
	s_mov_b32 s46, 0x18000
	s_mov_b32 s47, 0x20000
	s_mov_b32 s48, 0x28000
	s_mov_b32 s49, 0x30000
	s_mov_b32 s50, 0x38000
	v_add_u32_e32 v52, 0x420, v51
	v_add_u32_e32 v53, 0x428, v51
	v_add_u32_e32 v54, 0x840, v51
	v_add_u32_e32 v55, 0x848, v51
	v_add_u32_e32 v56, 0xc60, v51
	v_add_u32_e32 v57, 0xc68, v51
	v_add_u32_e32 v58, 0x1080, v51
	v_add_u32_e32 v59, 0x1088, v51
	v_add_u32_e32 v60, 0x14a0, v51
	v_add_u32_e32 v61, 0x14a8, v51
	v_add_u32_e32 v62, 0x18c0, v51
	v_add_u32_e32 v63, 0x18c8, v51
	v_add_u32_e32 v64, 0x1ce0, v51
	v_add_u32_e32 v65, 0x1ce8, v51
	s_mov_b64 s[8:9], 0x1880000
	s_movk_i32 s38, 0x5800
	s_mov_b32 s39, 0x2c000
	s_mov_b32 s51, 0x58000
	s_mov_b32 s52, 0x84000
	s_mov_b32 s53, 0xb0000
	s_mov_b32 s54, 0xdc000
	s_mov_b64 s[10:11], 0xd80000
	s_mov_b64 s[12:13], 0xb80000
	s_mov_b64 s[14:15], 0xa80000
	s_mov_b64 s[16:17], 0x980000
	s_mov_b64 s[18:19], 0x900000
	v_lshlrev_b32_e32 v38, 2, v2
	v_lshlrev_b32_e32 v40, 1, v4
	v_add_u32_e32 v66, v3, v6
	s_mov_b32 s55, 0
	s_branch .LBB0_518

; #define LAS __attribute__((address_space(3)))
; __device__ __forceinline__ unsigned cvtpk(float lo, float hi) { f32x2 v = {lo, hi}; bf16x2_t b = __builtin_convertvector(v, bf16x2_t); return __builtin_bit_cast(unsigned, b); }
; __device__ __forceinline__ void tr_item(const float* __restrict__ W, int ldw, int K, bf16* __restrict__ WT, int nblk, int mapmode, const float* __restrict__ ksc, LAS float* scr, int item, int lane) {
;     const int kb = item / nblk, nb = item - kb * nblk, k0 = 64 * kb, n0 = 32 * nb;
;     const int L = (n0 & ~255) + 64 * ((n0 >> 5) & 3) + 32 * ((n0 >> 7) & 1);
;     const int src0 = mapmode ? ((L >> 5) & 1) * DFF + 128 * (L >> 8) + 32 * ((L >> 6) & 3) : L;
;     f32x4 v[8];
; #pragma unroll
;     for (int i = 0; i < 8; ++i) { const int kk = 8 * i + (lane >> 3); v[i] = __builtin_nontemporal_load((const f32x4*)(W + (size_t)(k0 + kk) * ldw + src0 + 4 * (lane & 7))); }
; #pragma unroll
;     for (int i = 0; i < 8; ++i) { const int kk = 8 * i + (lane >> 3); f32x4 w = v[i]; if (ksc) w *= ksc[k0 + kk];
;         LAS float* d = scr + kk * 33 + 4 * (lane & 7); d[0] = w[0]; d[1] = w[1]; d[2] = w[2]; d[3] = w[3]; }
;     asm volatile("s_waitcnt lgkmcnt(0)" ::: "memory");
;     const int c = lane & 7;
; #pragma unroll
;     for (int j = 0; j < 4; ++j) { const int n = (lane >> 3) + 8 * j; const LAS float* s = scr + (8 * c) * 33 + n;
;         u32x4 o; o.x = cvtpk(s[0 * 33], s[1 * 33]); o.y = cvtpk(s[2 * 33], s[3 * 33]); o.z = cvtpk(s[4 * 33], s[5 * 33]); o.w = cvtpk(s[6 * 33], s[7 * 33]);
;         *(u32x4*)(WT + (size_t)(n0 + n) * K + k0 + 8 * c) = o; }
;     asm volatile("s_waitcnt lgkmcnt(0)" ::: "memory");
.LBB0_518:
	s_cmpk_gt_i32 s28, 0x7f
	s_mov_b64 s[4:5], -1
	s_cbranch_scc0 .LBB0_552
	s_cmpk_gt_u32 s28, 0x17f
	s_cbranch_scc0 .LBB0_549
	s_cmpk_gt_u32 s28, 0x27f
	s_cbranch_scc0 .LBB0_546
	s_cmpk_gt_u32 s28, 0x47f
	s_cbranch_scc0 .LBB0_543
	s_cmpk_gt_u32 s28, 0xf7f
	s_cbranch_scc0 .LBB0_524
	s_mov_b64 s[4:5], s[0:1]
	s_mov_b64 s[4:5], s[60:61]
	s_lshl_b32 s22, s28, 5
	s_lshl_b32 s25, s28, 3
	s_and_b32 s23, s22, 0x3e0
	s_lshl_b32 s24, s28, 6
	s_and_b32 s25, s25, 32
	s_and_b32 s22, s22, 0x300
	s_and_b32 s24, s24, 0xc0
	s_or_b32 s22, s25, s22
	s_and_b32 s6, s37, 0x7fffffc0
	s_or_b32 s22, s22, s24
	s_addk_i32 s6, 0xe100
	s_lshl_b32 s22, s22, 2
	s_waitcnt lgkmcnt(0)
	s_add_u32 s4, s4, s22
	v_or_b32_e32 v4, s6, v1
	s_addc_u32 s5, s5, 0
	v_lshl_add_u64 v[2:3], s[4:5], 0, v[38:39]
	v_lshlrev_b32_e32 v4, 10, v4
	v_mov_b32_e32 v5, v39
	v_lshl_add_u64 v[30:31], v[4:5], 2, v[2:3]
	v_add_co_u32_e32 v6, vcc, s44, v30
	s_mov_b64 s[20:21], s[0:1]
	s_nop 0
	v_addc_co_u32_e32 v7, vcc, 0, v31, vcc
	v_add_co_u32_e32 v10, vcc, s45, v30
	global_load_dwordx4 v[2:5], v[30:31], off nt
	s_nop 0
	global_load_dwordx4 v[6:9], v[6:7], off nt
	v_addc_co_u32_e32 v11, vcc, 0, v31, vcc
	v_add_co_u32_e32 v14, vcc, s46, v30
	v_mov_b32_e32 v41, v39
	s_nop 0
	v_addc_co_u32_e32 v15, vcc, 0, v31, vcc
	v_add_co_u32_e32 v18, vcc, s47, v30
	global_load_dwordx4 v[10:13], v[10:11], off nt
	s_nop 0
	global_load_dwordx4 v[14:17], v[14:15], off nt
	v_addc_co_u32_e32 v19, vcc, 0, v31, vcc
	v_add_co_u32_e32 v22, vcc, s48, v30
	v_or_b32_e32 v34, s23, v1
	s_nop 0
	v_addc_co_u32_e32 v23, vcc, 0, v31, vcc
	global_load_dwordx4 v[18:21], v[18:19], off nt
	s_nop 0
	global_load_dwordx4 v[22:25], v[22:23], off nt
	v_add_co_u32_e32 v26, vcc, s49, v30
	s_mov_b64 s[4:5], s[74:75]
	s_nop 0
	v_addc_co_u32_e32 v27, vcc, 0, v31, vcc
	global_load_dwordx4 v[26:29], v[26:27], off nt
	v_add_co_u32_e32 v30, vcc, s50, v30
	s_lshl_b64 s[20:21], s[6:7], 1
	s_nop 0
	v_addc_co_u32_e32 v31, vcc, 0, v31, vcc
	global_load_dwordx4 v[30:33], v[30:31], off nt
	s_waitcnt lgkmcnt(0)
	s_add_u32 s4, s4, s20
	s_addc_u32 s5, s5, s21
	v_lshl_add_u64 v[36:37], s[4:5], 0, v[40:41]
	v_mov_b32_e32 v35, v39
	v_mul_u32_u24_e32 v34, 0x1600, v34
	v_lshl_add_u64 v[36:37], v[36:37], 0, s[8:9]
	s_mov_b64 s[4:5], 0
	s_waitcnt vmcnt(4)
	ds_write2_b32 v51, v2, v3 offset1:1
	ds_write2_b32 v51, v4, v5 offset0:2 offset1:3
	ds_write2_b32 v52, v6, v7 offset1:1
	ds_write2_b32 v53, v8, v9 offset1:1
	ds_write2_b32 v54, v10, v11 offset1:1
	ds_write2_b32 v55, v12, v13 offset1:1
	ds_write2_b32 v56, v14, v15 offset1:1
	ds_write2_b32 v57, v16, v17 offset1:1
	s_waitcnt vmcnt(3)
	ds_write2_b32 v58, v18, v19 offset1:1
	ds_write2_b32 v59, v20, v21 offset1:1
	s_waitcnt vmcnt(2)
	ds_write2_b32 v60, v22, v23 offset1:1
	ds_write2_b32 v61, v24, v25 offset1:1
	s_waitcnt vmcnt(1)
	ds_write2_b32 v62, v26, v27 offset1:1
	ds_write2_b32 v63, v28, v29 offset1:1
	s_waitcnt vmcnt(0)
	ds_write2_b32 v64, v30, v31 offset1:1
	ds_write2_b32 v65, v32, v33 offset1:1
	s_waitcnt lgkmcnt(0)
	ds_read2_b32 v[6:7], v49 offset0:33 offset1:41
	ds_read2_b32 v[8:9], v49 offset1:8
	ds_read2_b32 v[10:11], v49 offset0:66 offset1:74
	ds_read2_b32 v[12:13], v49 offset0:99 offset1:107
	ds_read2_b32 v[14:15], v49 offset0:132 offset1:140
	ds_read2_b32 v[16:17], v49 offset0:165 offset1:173
	ds_read2_b32 v[18:19], v49 offset0:198 offset1:206
	ds_read2_b32 v[20:21], v49 offset0:231 offset1:239
	v_lshl_add_u64 v[22:23], v[36:37], 0, v[34:35]
	s_waitcnt lgkmcnt(6)
	v_cvt_pk_bf16_f32 v2, v8, v6
	s_waitcnt lgkmcnt(4)
	v_cvt_pk_bf16_f32 v3, v10, v12
	s_waitcnt lgkmcnt(2)
	v_cvt_pk_bf16_f32 v4, v14, v16
	s_waitcnt lgkmcnt(0)
	v_cvt_pk_bf16_f32 v5, v18, v20
	global_store_dwordx4 v[22:23], v[2:5], off
	v_or_b32_e32 v6, s23, v46
	v_mul_u32_u24_e32 v6, 0x1600, v6
	v_cvt_pk_bf16_f32 v2, v9, v7
	v_cvt_pk_bf16_f32 v3, v11, v13
	v_cvt_pk_bf16_f32 v4, v15, v17
	v_cvt_pk_bf16_f32 v5, v19, v21
	ds_read2_b32 v[8:9], v49 offset0:16 offset1:24
	ds_read2_b32 v[10:11], v49 offset0:49 offset1:57
	ds_read2_b32 v[12:13], v49 offset0:82 offset1:90
	ds_read2_b32 v[14:15], v49 offset0:115 offset1:123
	ds_read2_b32 v[16:17], v49 offset0:148 offset1:156
	ds_read2_b32 v[18:19], v49 offset0:181 offset1:189
	ds_read2_b32 v[20:21], v49 offset0:214 offset1:222
	ds_read2_b32 v[22:23], v49 offset0:247 offset1:255
	v_mov_b32_e32 v7, v39
	v_lshl_add_u64 v[6:7], v[36:37], 0, v[6:7]
	global_store_dwordx4 v[6:7], v[2:5], off
	v_or_b32_e32 v6, s23, v47
	v_mul_u32_u24_e32 v6, 0x1600, v6
	v_mov_b32_e32 v7, v39
	s_waitcnt lgkmcnt(6)
	v_cvt_pk_bf16_f32 v2, v8, v10
	s_waitcnt lgkmcnt(4)
	v_cvt_pk_bf16_f32 v3, v12, v14
	s_waitcnt lgkmcnt(2)
	v_cvt_pk_bf16_f32 v4, v16, v18
	s_waitcnt lgkmcnt(0)
	v_cvt_pk_bf16_f32 v5, v20, v22
	v_lshl_add_u64 v[6:7], v[36:37], 0, v[6:7]
	global_store_dwordx4 v[6:7], v[2:5], off
	v_or_b32_e32 v6, s23, v48
	v_mul_u32_u24_e32 v6, 0x1600, v6
	v_mov_b32_e32 v7, v39
	v_cvt_pk_bf16_f32 v2, v9, v11
	v_cvt_pk_bf16_f32 v3, v13, v15
	v_cvt_pk_bf16_f32 v4, v17, v19
	v_cvt_pk_bf16_f32 v5, v21, v23
	v_lshl_add_u64 v[6:7], v[36:37], 0, v[6:7]
	global_store_dwordx4 v[6:7], v[2:5], off
	s_waitcnt lgkmcnt(0)
; #define LAS __attribute__((address_space(3)))
; __device__ __forceinline__ void tr_item(const float* __restrict__ W, int ldw, int K, bf16* __restrict__ WT, int nblk, int mapmode, const float* __restrict__ ksc, LAS float* scr, int item, int lane) {
;     const int kb = item / nblk, nb = item - kb * nblk, k0 = 64 * kb, n0 = 32 * nb;
;     const int L = (n0 & ~255) + 64 * ((n0 >> 5) & 3) + 32 * ((n0 >> 7) & 1);
;     const int src0 = mapmode ? ((L >> 5) & 1) * DFF + 128 * (L >> 8) + 32 * ((L >> 6) & 3) : L;
;     f32x4 v[8];
; #pragma unroll
;     for (int i = 0; i < 8; ++i) { const int kk = 8 * i + (lane >> 3); v[i] = __builtin_nontemporal_load((const f32x4*)(W + (size_t)(k0 + kk) * ldw + src0 + 4 * (lane & 7))); }
; #pragma unroll
;     for (int i = 0; i < 8; ++i) { const int kk = 8 * i + (lane >> 3); f32x4 w = v[i]; if (ksc) w *= ksc[k0 + kk];
;         LAS float* d = scr + kk * 33 + 4 * (lane & 7); d[0] = w[0]; d[1] = w[1]; d[2] = w[2]; d[3] = w[3]; }
.LBB0_524:
	s_andn2_b64 vcc, exec, s[4:5]
	s_cbranch_vccnz .LBB0_542
	s_and_b32 s4, 0xffff, s41
	s_mul_hi_u32 s56, s4, 0x1745d18
	s_mul_i32 s6, s28, 0xba2f
	s_mul_i32 s4, s56, 0xb00
	s_add_i32 s6, s6, 0xfcba2c80
	s_sub_i32 s24, s42, s4
	s_mov_b64 s[4:5], s[0:1]
	s_lshr_b32 s6, s6, 17
	s_bfe_i32 s25, s28, 0x10002
	s_mov_b64 s[20:21], s[62:63]
	s_and_b32 s57, s6, 0x7fc0
	s_add_i32 s6, s30, s55
	s_and_b32 s25, s25, 0xb00
	s_and_b32 s24, s24, 0xffffff80
	s_add_i32 s24, s24, s25
	s_and_b32 s25, s6, 0x60
	s_or_b32 s24, s24, s25
	s_ashr_i32 s25, s24, 31
	s_lshl_b64 s[24:25], s[24:25], 2
	v_or_b32_e32 v42, s57, v1
	s_waitcnt lgkmcnt(0)
	s_add_u32 s20, s20, s24
	s_addc_u32 s21, s21, s25
	v_mul_u32_u24_e32 v6, 0x1600, v42
	v_lshl_add_u64 v[2:3], s[20:21], 0, v[38:39]
	v_lshlrev_b32_e32 v6, 2, v6
	v_mov_b32_e32 v7, v39
	v_mad_u64_u32 v[4:5], s[20:21], v42, s38, v[2:3]
	v_lshl_add_u64 v[2:3], v[2:3], 0, v[6:7]
	v_add_co_u32_e32 v6, vcc, s39, v2
	s_mov_b64 s[4:5], s[0:1]
	s_mov_b64 s[22:23], s[0:1]
	v_addc_co_u32_e32 v7, vcc, 0, v3, vcc
	global_load_dwordx4 v[26:29], v[4:5], off nt
	global_load_dwordx4 v[30:33], v[6:7], off nt
	v_add_co_u32_e32 v4, vcc, s51, v2
	s_mov_b64 s[26:27], -1
	s_nop 0
	v_addc_co_u32_e32 v5, vcc, 0, v3, vcc
	v_add_co_u32_e32 v6, vcc, s52, v2
	v_add_lshl_u32 v41, s57, v1, 2
	s_nop 0
	v_addc_co_u32_e32 v7, vcc, 0, v3, vcc
	global_load_dwordx4 v[18:21], v[4:5], off nt
	global_load_dwordx4 v[22:25], v[6:7], off nt
	v_add_co_u32_e32 v4, vcc, s53, v2
	s_nop 1
	v_addc_co_u32_e32 v5, vcc, 0, v3, vcc
	v_add_co_u32_e32 v6, vcc, s54, v2
	s_nop 1
	v_addc_co_u32_e32 v7, vcc, 0, v3, vcc
	global_load_dwordx4 v[10:13], v[4:5], off nt
	global_load_dwordx4 v[14:17], v[6:7], off nt
	v_add_co_u32_e32 v4, vcc, 0x108000, v2
	s_nop 1
	v_addc_co_u32_e32 v5, vcc, 0, v3, vcc
	v_add_co_u32_e32 v6, vcc, 0x134000, v2
	s_nop 1
	v_addc_co_u32_e32 v7, vcc, 0, v3, vcc
	global_load_dwordx4 v[2:5], v[4:5], off nt
	s_nop 0
	global_load_dwordx4 v[6:9], v[6:7], off nt
	s_mov_b64 s[22:23], s[64:65]
	s_waitcnt lgkmcnt(0)
	s_cmp_lg_u64 s[22:23], 0
	s_cselect_b64 s[24:25], -1, 0
	s_cmp_eq_u64 s[22:23], 0
	s_cbranch_scc1 .LBB0_527
	v_lshlrev_b32_e32 v34, 2, v42
	global_load_dword v34, v34, s[22:23]
	s_nop 0
	global_load_dword v68, v41, s[22:23] offset:32
	s_mov_b64 s[26:27], 0
	s_waitcnt vmcnt(0)
	v_pk_mul_f32 v[42:43], v[28:29], v[34:35] op_sel_hi:[1,0]
	v_pk_mul_f32 v[44:45], v[26:27], v[34:35] op_sel_hi:[1,0]
	v_pk_mul_f32 v[36:37], v[32:33], v[68:69] op_sel_hi:[1,0]
	v_pk_mul_f32 v[34:35], v[30:31], v[68:69] op_sel_hi:[1,0]
.LBB0_527:
	s_mov_b64 s[20:21], s[74:75]
	s_andn2_b64 vcc, exec, s[26:27]
	s_cbranch_vccnz .LBB0_529
	s_waitcnt vmcnt(0)
	v_mov_b64_e32 v[36:37], v[32:33]
	v_mov_b64_e32 v[34:35], v[30:31]
	v_mov_b32_e32 v44, v26
	v_mov_b32_e32 v45, v27
	v_mov_b32_e32 v42, v28
	v_mov_b32_e32 v43, v29

; #define LAS __attribute__((address_space(3)))
; __device__ __forceinline__ unsigned cvtpk(float lo, float hi) { f32x2 v = {lo, hi}; bf16x2_t b = __builtin_convertvector(v, bf16x2_t); return __builtin_bit_cast(unsigned, b); }
; __device__ __forceinline__ void tr_item(const float* __restrict__ W, int ldw, int K, bf16* __restrict__ WT, int nblk, int mapmode, const float* __restrict__ ksc, LAS float* scr, int item, int lane) {
;     const int kb = item / nblk, nb = item - kb * nblk, k0 = 64 * kb, n0 = 32 * nb;
;     const int L = (n0 & ~255) + 64 * ((n0 >> 5) & 3) + 32 * ((n0 >> 7) & 1);
;     const int src0 = mapmode ? ((L >> 5) & 1) * DFF + 128 * (L >> 8) + 32 * ((L >> 6) & 3) : L;
;     f32x4 v[8];
; #pragma unroll
;     for (int i = 0; i < 8; ++i) { const int kk = 8 * i + (lane >> 3); v[i] = __builtin_nontemporal_load((const f32x4*)(W + (size_t)(k0 + kk) * ldw + src0 + 4 * (lane & 7))); }
; #pragma unroll
;     for (int i = 0; i < 8; ++i) { const int kk = 8 * i + (lane >> 3); f32x4 w = v[i]; if (ksc) w *= ksc[k0 + kk];
;         LAS float* d = scr + kk * 33 + 4 * (lane & 7); d[0] = w[0]; d[1] = w[1]; d[2] = w[2]; d[3] = w[3]; }
;     asm volatile("s_waitcnt lgkmcnt(0)" ::: "memory");
;     const int c = lane & 7;
; #pragma unroll
;     for (int j = 0; j < 4; ++j) { const int n = (lane >> 3) + 8 * j; const LAS float* s = scr + (8 * c) * 33 + n;
;         u32x4 o; o.x = cvtpk(s[0 * 33], s[1 * 33]); o.y = cvtpk(s[2 * 33], s[3 * 33]); o.z = cvtpk(s[4 * 33], s[5 * 33]); o.w = cvtpk(s[6 * 33], s[7 * 33]);
;         *(u32x4*)(WT + (size_t)(n0 + n) * K + k0 + 8 * c) = o; }
;     asm volatile("s_waitcnt lgkmcnt(0)" ::: "memory");
.LBB0_543:
	s_andn2_b64 vcc, exec, s[4:5]
	s_cbranch_vccnz .LBB0_545
	s_mov_b64 s[4:5], s[0:1]
	s_mov_b64 s[4:5], s[66:67]
	s_add_i32 s22, s30, s55
	s_and_b32 s23, s22, 0x3e0
	s_and_b32 s25, s33, 32
	s_and_b32 s22, s22, 0x300
	s_and_b32 s24, s35, 0xc0
	s_or_b32 s22, s25, s22
	s_and_b32 s6, s37, 0xfc0
	s_or_b32 s22, s22, s24
	s_addk_i32 s6, 0xfb00
	s_lshl_b32 s22, s22, 2
	s_waitcnt lgkmcnt(0)
	s_add_u32 s4, s4, s22
	v_or_b32_e32 v4, s6, v1
	s_addc_u32 s5, s5, 0
	v_lshl_add_u64 v[2:3], s[4:5], 0, v[38:39]
	v_lshlrev_b32_e32 v4, 10, v4
	v_mov_b32_e32 v5, v39
	v_lshl_add_u64 v[30:31], v[4:5], 2, v[2:3]
	v_add_co_u32_e32 v6, vcc, s44, v30
	s_mov_b64 s[20:21], s[0:1]
	s_nop 0
	v_addc_co_u32_e32 v7, vcc, 0, v31, vcc
	v_add_co_u32_e32 v10, vcc, s45, v30
	global_load_dwordx4 v[2:5], v[30:31], off nt
	s_nop 0
	global_load_dwordx4 v[6:9], v[6:7], off nt
	v_addc_co_u32_e32 v11, vcc, 0, v31, vcc
	v_add_co_u32_e32 v14, vcc, s46, v30
	v_mov_b32_e32 v41, v39
	s_nop 0
	v_addc_co_u32_e32 v15, vcc, 0, v31, vcc
	v_add_co_u32_e32 v18, vcc, s47, v30
	global_load_dwordx4 v[10:13], v[10:11], off nt
	s_nop 0
	global_load_dwordx4 v[14:17], v[14:15], off nt
	v_addc_co_u32_e32 v19, vcc, 0, v31, vcc
	v_add_co_u32_e32 v22, vcc, s48, v30
	v_or_b32_e32 v34, s23, v1
	s_nop 0
	v_addc_co_u32_e32 v23, vcc, 0, v31, vcc
	global_load_dwordx4 v[18:21], v[18:19], off nt
	s_nop 0
	global_load_dwordx4 v[22:25], v[22:23], off nt
	v_add_co_u32_e32 v26, vcc, s49, v30
	s_mov_b64 s[4:5], s[74:75]
	s_nop 0
	v_addc_co_u32_e32 v27, vcc, 0, v31, vcc
	global_load_dwordx4 v[26:29], v[26:27], off nt
	v_add_co_u32_e32 v30, vcc, s50, v30
	s_lshl_b64 s[20:21], s[6:7], 1
	s_nop 0
	v_addc_co_u32_e32 v31, vcc, 0, v31, vcc
	global_load_dwordx4 v[30:33], v[30:31], off nt
	s_waitcnt lgkmcnt(0)
	s_add_u32 s4, s4, s20
	s_addc_u32 s5, s5, s21
	v_lshl_add_u64 v[36:37], s[4:5], 0, v[40:41]
	v_mov_b32_e32 v35, v39
	v_lshlrev_b32_e32 v34, 11, v34
	v_lshl_add_u64 v[36:37], v[36:37], 0, s[12:13]
	s_waitcnt vmcnt(4)
	ds_write2_b32 v51, v2, v3 offset1:1
	ds_write2_b32 v51, v4, v5 offset0:2 offset1:3
	ds_write2_b32 v52, v6, v7 offset1:1
	ds_write2_b32 v53, v8, v9 offset1:1
	ds_write2_b32 v54, v10, v11 offset1:1
	ds_write2_b32 v55, v12, v13 offset1:1
	ds_write2_b32 v56, v14, v15 offset1:1
	ds_write2_b32 v57, v16, v17 offset1:1
	s_waitcnt vmcnt(3)
	ds_write2_b32 v58, v18, v19 offset1:1
	ds_write2_b32 v59, v20, v21 offset1:1
	s_waitcnt vmcnt(2)
	ds_write2_b32 v60, v22, v23 offset1:1
	ds_write2_b32 v61, v24, v25 offset1:1
	s_waitcnt vmcnt(1)
	ds_write2_b32 v62, v26, v27 offset1:1
	ds_write2_b32 v63, v28, v29 offset1:1
	s_waitcnt vmcnt(0)
	ds_write2_b32 v64, v30, v31 offset1:1
	ds_write2_b32 v65, v32, v33 offset1:1
	s_waitcnt lgkmcnt(0)
	ds_read2_b32 v[6:7], v49 offset0:33 offset1:41
	ds_read2_b32 v[8:9], v49 offset1:8
	ds_read2_b32 v[10:11], v49 offset0:66 offset1:74
	ds_read2_b32 v[12:13], v49 offset0:99 offset1:107
	ds_read2_b32 v[14:15], v49 offset0:132 offset1:140
	ds_read2_b32 v[16:17], v49 offset0:165 offset1:173
	ds_read2_b32 v[18:19], v49 offset0:198 offset1:206
	ds_read2_b32 v[20:21], v49 offset0:231 offset1:239
	v_lshl_add_u64 v[22:23], v[36:37], 0, v[34:35]
	s_waitcnt lgkmcnt(6)
	v_cvt_pk_bf16_f32 v2, v8, v6
	s_waitcnt lgkmcnt(4)
	v_cvt_pk_bf16_f32 v3, v10, v12
	s_waitcnt lgkmcnt(2)
	v_cvt_pk_bf16_f32 v4, v14, v16
	s_waitcnt lgkmcnt(0)
	v_cvt_pk_bf16_f32 v5, v18, v20
	global_store_dwordx4 v[22:23], v[2:5], off
	v_cvt_pk_bf16_f32 v6, v9, v7
	v_cvt_pk_bf16_f32 v7, v11, v13
	v_cvt_pk_bf16_f32 v8, v15, v17
	v_cvt_pk_bf16_f32 v9, v19, v21
	v_or_b32_e32 v2, s23, v46
	ds_read2_b32 v[10:11], v49 offset0:49 offset1:57
	ds_read2_b32 v[12:13], v49 offset0:16 offset1:24
	ds_read2_b32 v[14:15], v49 offset0:82 offset1:90
	ds_read2_b32 v[16:17], v49 offset0:115 offset1:123
	ds_read2_b32 v[18:19], v49 offset0:148 offset1:156
	ds_read2_b32 v[20:21], v49 offset0:181 offset1:189
	ds_read2_b32 v[22:23], v49 offset0:214 offset1:222
	ds_read2_b32 v[24:25], v49 offset0:247 offset1:255
	v_lshlrev_b32_e32 v2, 11, v2
	v_mov_b32_e32 v3, v39
	v_lshl_add_u64 v[2:3], v[36:37], 0, v[2:3]
	global_store_dwordx4 v[2:3], v[6:9], off
	s_waitcnt lgkmcnt(6)
	v_cvt_pk_bf16_f32 v2, v12, v10
	s_waitcnt lgkmcnt(4)
	v_cvt_pk_bf16_f32 v3, v14, v16
	v_or_b32_e32 v6, s23, v47
	v_lshlrev_b32_e32 v6, 11, v6
	v_mov_b32_e32 v7, v39
	s_waitcnt lgkmcnt(2)
	v_cvt_pk_bf16_f32 v4, v18, v20
	s_waitcnt lgkmcnt(0)
	v_cvt_pk_bf16_f32 v5, v22, v24
	v_lshl_add_u64 v[6:7], v[36:37], 0, v[6:7]
	global_store_dwordx4 v[6:7], v[2:5], off
	v_or_b32_e32 v6, s23, v48
	v_lshlrev_b32_e32 v6, 11, v6
	v_mov_b32_e32 v7, v39
	v_cvt_pk_bf16_f32 v2, v13, v11
	v_cvt_pk_bf16_f32 v3, v15, v17
	v_cvt_pk_bf16_f32 v4, v19, v21
	v_cvt_pk_bf16_f32 v5, v23, v25
	v_lshl_add_u64 v[6:7], v[36:37], 0, v[6:7]
	global_store_dwordx4 v[6:7], v[2:5], off
	s_waitcnt lgkmcnt(0)

; #define LAS __attribute__((address_space(3)))
; __device__ __forceinline__ unsigned cvtpk(float lo, float hi) { f32x2 v = {lo, hi}; bf16x2_t b = __builtin_convertvector(v, bf16x2_t); return __builtin_bit_cast(unsigned, b); }
; __device__ __forceinline__ void tr_item(const float* __restrict__ W, int ldw, int K, bf16* __restrict__ WT, int nblk, int mapmode, const float* __restrict__ ksc, LAS float* scr, int item, int lane) {
;     const int kb = item / nblk, nb = item - kb * nblk, k0 = 64 * kb, n0 = 32 * nb;
;     const int L = (n0 & ~255) + 64 * ((n0 >> 5) & 3) + 32 * ((n0 >> 7) & 1);
;     const int src0 = mapmode ? ((L >> 5) & 1) * DFF + 128 * (L >> 8) + 32 * ((L >> 6) & 3) : L;
;     f32x4 v[8];
; #pragma unroll
;     for (int i = 0; i < 8; ++i) { const int kk = 8 * i + (lane >> 3); v[i] = __builtin_nontemporal_load((const f32x4*)(W + (size_t)(k0 + kk) * ldw + src0 + 4 * (lane & 7))); }
; #pragma unroll
;     for (int i = 0; i < 8; ++i) { const int kk = 8 * i + (lane >> 3); f32x4 w = v[i]; if (ksc) w *= ksc[k0 + kk];
;         LAS float* d = scr + kk * 33 + 4 * (lane & 7); d[0] = w[0]; d[1] = w[1]; d[2] = w[2]; d[3] = w[3]; }
;     asm volatile("s_waitcnt lgkmcnt(0)" ::: "memory");
;     const int c = lane & 7;
; #pragma unroll
;     for (int j = 0; j < 4; ++j) { const int n = (lane >> 3) + 8 * j; const LAS float* s = scr + (8 * c) * 33 + n;
;         u32x4 o; o.x = cvtpk(s[0 * 33], s[1 * 33]); o.y = cvtpk(s[2 * 33], s[3 * 33]); o.z = cvtpk(s[4 * 33], s[5 * 33]); o.w = cvtpk(s[6 * 33], s[7 * 33]);
;         *(u32x4*)(WT + (size_t)(n0 + n) * K + k0 + 8 * c) = o; }
;     asm volatile("s_waitcnt lgkmcnt(0)" ::: "memory");
.LBB0_546:
	s_andn2_b64 vcc, exec, s[4:5]
	s_cbranch_vccnz .LBB0_548
	s_mov_b64 s[4:5], s[0:1]
	s_mov_b64 s[4:5], s[68:69]
	s_add_i32 s22, s30, s55
	s_and_b32 s23, s22, 0x3e0
	s_and_b32 s25, s33, 32
	s_and_b32 s22, s22, 0x300
	s_and_b32 s24, s35, 0xc0
	s_or_b32 s22, s25, s22
	s_and_b32 s6, s37, 0x7c0
	s_or_b32 s22, s22, s24
	s_addk_i32 s6, 0xfd00
	s_lshl_b32 s22, s22, 2
	s_waitcnt lgkmcnt(0)
	s_add_u32 s4, s4, s22
	v_or_b32_e32 v4, s6, v1
	s_addc_u32 s5, s5, 0
	v_lshl_add_u64 v[2:3], s[4:5], 0, v[38:39]
	v_lshlrev_b32_e32 v4, 10, v4
	v_mov_b32_e32 v5, v39
	v_lshl_add_u64 v[30:31], v[4:5], 2, v[2:3]
	v_add_co_u32_e32 v6, vcc, s44, v30
	s_mov_b64 s[20:21], s[0:1]
	s_nop 0
	v_addc_co_u32_e32 v7, vcc, 0, v31, vcc
	v_add_co_u32_e32 v10, vcc, s45, v30
	global_load_dwordx4 v[2:5], v[30:31], off nt
	s_nop 0
	global_load_dwordx4 v[6:9], v[6:7], off nt
	v_addc_co_u32_e32 v11, vcc, 0, v31, vcc
	v_add_co_u32_e32 v14, vcc, s46, v30
	v_mov_b32_e32 v41, v39
	s_nop 0
	v_addc_co_u32_e32 v15, vcc, 0, v31, vcc
	v_add_co_u32_e32 v18, vcc, s47, v30
	global_load_dwordx4 v[10:13], v[10:11], off nt
	s_nop 0
	global_load_dwordx4 v[14:17], v[14:15], off nt
	v_addc_co_u32_e32 v19, vcc, 0, v31, vcc
	v_add_co_u32_e32 v22, vcc, s48, v30
	v_or_b32_e32 v34, s23, v1
	s_nop 0
	v_addc_co_u32_e32 v23, vcc, 0, v31, vcc
	global_load_dwordx4 v[18:21], v[18:19], off nt
	s_nop 0
	global_load_dwordx4 v[22:25], v[22:23], off nt
	v_add_co_u32_e32 v26, vcc, s49, v30
	s_mov_b64 s[4:5], s[74:75]
	s_nop 0
	v_addc_co_u32_e32 v27, vcc, 0, v31, vcc
	global_load_dwordx4 v[26:29], v[26:27], off nt
	v_add_co_u32_e32 v30, vcc, s50, v30
	s_lshl_b64 s[20:21], s[6:7], 1
	s_nop 0
	v_addc_co_u32_e32 v31, vcc, 0, v31, vcc
	global_load_dwordx4 v[30:33], v[30:31], off nt
	s_waitcnt lgkmcnt(0)
	s_add_u32 s4, s4, s20
	s_addc_u32 s5, s5, s21
	v_lshl_add_u64 v[36:37], s[4:5], 0, v[40:41]
	v_mov_b32_e32 v35, v39
	v_lshlrev_b32_e32 v34, 10, v34
	v_lshl_add_u64 v[36:37], v[36:37], 0, s[14:15]
	s_waitcnt vmcnt(4)
	ds_write2_b32 v51, v2, v3 offset1:1
	ds_write2_b32 v51, v4, v5 offset0:2 offset1:3
	ds_write2_b32 v52, v6, v7 offset1:1
	ds_write2_b32 v53, v8, v9 offset1:1
	ds_write2_b32 v54, v10, v11 offset1:1
	ds_write2_b32 v55, v12, v13 offset1:1
	ds_write2_b32 v56, v14, v15 offset1:1
	ds_write2_b32 v57, v16, v17 offset1:1
	s_waitcnt vmcnt(3)
	ds_write2_b32 v58, v18, v19 offset1:1
	ds_write2_b32 v59, v20, v21 offset1:1
	s_waitcnt vmcnt(2)
	ds_write2_b32 v60, v22, v23 offset1:1
	ds_write2_b32 v61, v24, v25 offset1:1
	s_waitcnt vmcnt(1)
	ds_write2_b32 v62, v26, v27 offset1:1
	ds_write2_b32 v63, v28, v29 offset1:1
	s_waitcnt vmcnt(0)
	ds_write2_b32 v64, v30, v31 offset1:1
	ds_write2_b32 v65, v32, v33 offset1:1
	s_waitcnt lgkmcnt(0)
	ds_read2_b32 v[6:7], v49 offset0:33 offset1:41
	ds_read2_b32 v[8:9], v49 offset1:8
	ds_read2_b32 v[10:11], v49 offset0:66 offset1:74
	ds_read2_b32 v[12:13], v49 offset0:99 offset1:107
	ds_read2_b32 v[14:15], v49 offset0:132 offset1:140
	ds_read2_b32 v[16:17], v49 offset0:165 offset1:173
	ds_read2_b32 v[18:19], v49 offset0:198 offset1:206
	ds_read2_b32 v[20:21], v49 offset0:231 offset1:239
	v_lshl_add_u64 v[22:23], v[36:37], 0, v[34:35]
	s_waitcnt lgkmcnt(6)
	v_cvt_pk_bf16_f32 v2, v8, v6
	s_waitcnt lgkmcnt(4)
	v_cvt_pk_bf16_f32 v3, v10, v12
	s_waitcnt lgkmcnt(2)
	v_cvt_pk_bf16_f32 v4, v14, v16
	s_waitcnt lgkmcnt(0)
	v_cvt_pk_bf16_f32 v5, v18, v20
	global_store_dwordx4 v[22:23], v[2:5], off
	v_cvt_pk_bf16_f32 v6, v9, v7
	v_cvt_pk_bf16_f32 v7, v11, v13
	v_cvt_pk_bf16_f32 v8, v15, v17
	v_cvt_pk_bf16_f32 v9, v19, v21
	v_or_b32_e32 v2, s23, v46
	ds_read2_b32 v[10:11], v49 offset0:49 offset1:57
	ds_read2_b32 v[12:13], v49 offset0:16 offset1:24
	ds_read2_b32 v[14:15], v49 offset0:82 offset1:90
	ds_read2_b32 v[16:17], v49 offset0:115 offset1:123
	ds_read2_b32 v[18:19], v49 offset0:148 offset1:156
	ds_read2_b32 v[20:21], v49 offset0:181 offset1:189
	ds_read2_b32 v[22:23], v49 offset0:214 offset1:222
	ds_read2_b32 v[24:25], v49 offset0:247 offset1:255
	v_lshlrev_b32_e32 v2, 10, v2
	v_mov_b32_e32 v3, v39
	v_lshl_add_u64 v[2:3], v[36:37], 0, v[2:3]
	global_store_dwordx4 v[2:3], v[6:9], off
	s_waitcnt lgkmcnt(6)
	v_cvt_pk_bf16_f32 v2, v12, v10
	s_waitcnt lgkmcnt(4)
	v_cvt_pk_bf16_f32 v3, v14, v16
	v_or_b32_e32 v6, s23, v47
	v_lshlrev_b32_e32 v6, 10, v6
	v_mov_b32_e32 v7, v39
	s_waitcnt lgkmcnt(2)
	v_cvt_pk_bf16_f32 v4, v18, v20
	s_waitcnt lgkmcnt(0)
	v_cvt_pk_bf16_f32 v5, v22, v24
	v_lshl_add_u64 v[6:7], v[36:37], 0, v[6:7]
	global_store_dwordx4 v[6:7], v[2:5], off
	v_or_b32_e32 v6, s23, v48
	v_lshlrev_b32_e32 v6, 10, v6
	v_mov_b32_e32 v7, v39
	v_cvt_pk_bf16_f32 v2, v13, v11
	v_cvt_pk_bf16_f32 v3, v15, v17
	v_cvt_pk_bf16_f32 v4, v19, v21
	v_cvt_pk_bf16_f32 v5, v23, v25
	v_lshl_add_u64 v[6:7], v[36:37], 0, v[6:7]
	global_store_dwordx4 v[6:7], v[2:5], off
	s_waitcnt lgkmcnt(0)

; #define LAS __attribute__((address_space(3)))
; __device__ __forceinline__ unsigned cvtpk(float lo, float hi) { f32x2 v = {lo, hi}; bf16x2_t b = __builtin_convertvector(v, bf16x2_t); return __builtin_bit_cast(unsigned, b); }
; __device__ __forceinline__ void tr_item(const float* __restrict__ W, int ldw, int K, bf16* __restrict__ WT, int nblk, int mapmode, const float* __restrict__ ksc, LAS float* scr, int item, int lane) {
;     const int kb = item / nblk, nb = item - kb * nblk, k0 = 64 * kb, n0 = 32 * nb;
;     const int L = (n0 & ~255) + 64 * ((n0 >> 5) & 3) + 32 * ((n0 >> 7) & 1);
;     const int src0 = mapmode ? ((L >> 5) & 1) * DFF + 128 * (L >> 8) + 32 * ((L >> 6) & 3) : L;
;     f32x4 v[8];
; #pragma unroll
;     for (int i = 0; i < 8; ++i) { const int kk = 8 * i + (lane >> 3); v[i] = __builtin_nontemporal_load((const f32x4*)(W + (size_t)(k0 + kk) * ldw + src0 + 4 * (lane & 7))); }
; #pragma unroll
;     for (int i = 0; i < 8; ++i) { const int kk = 8 * i + (lane >> 3); f32x4 w = v[i]; if (ksc) w *= ksc[k0 + kk];
;         LAS float* d = scr + kk * 33 + 4 * (lane & 7); d[0] = w[0]; d[1] = w[1]; d[2] = w[2]; d[3] = w[3]; }
;     asm volatile("s_waitcnt lgkmcnt(0)" ::: "memory");
;     const int c = lane & 7;
; #pragma unroll
;     for (int j = 0; j < 4; ++j) { const int n = (lane >> 3) + 8 * j; const LAS float* s = scr + (8 * c) * 33 + n;
;         u32x4 o; o.x = cvtpk(s[0 * 33], s[1 * 33]); o.y = cvtpk(s[2 * 33], s[3 * 33]); o.z = cvtpk(s[4 * 33], s[5 * 33]); o.w = cvtpk(s[6 * 33], s[7 * 33]);
;         *(u32x4*)(WT + (size_t)(n0 + n) * K + k0 + 8 * c) = o; }
;     asm volatile("s_waitcnt lgkmcnt(0)" ::: "memory");
.LBB0_549:
	s_andn2_b64 vcc, exec, s[4:5]
	s_cbranch_vccnz .LBB0_551
	s_mov_b64 s[4:5], s[0:1]
	s_mov_b64 s[4:5], s[70:71]
	s_add_i32 s22, s30, s55
	s_and_b32 s23, s22, 0x3e0
	s_and_b32 s25, s33, 32
	s_and_b32 s22, s22, 0x300
	s_and_b32 s24, s35, 0xc0
	s_or_b32 s22, s25, s22
	s_and_b32 s6, s37, 0x3c0
	s_or_b32 s22, s22, s24
	s_addk_i32 s6, 0xff00
	s_lshl_b32 s22, s22, 2
	s_waitcnt lgkmcnt(0)
	s_add_u32 s4, s4, s22
	v_or_b32_e32 v4, s6, v1
	s_addc_u32 s5, s5, 0
	v_lshl_add_u64 v[2:3], s[4:5], 0, v[38:39]
	v_lshlrev_b32_e32 v4, 10, v4
	v_mov_b32_e32 v5, v39
	v_lshl_add_u64 v[30:31], v[4:5], 2, v[2:3]
	v_add_co_u32_e32 v6, vcc, s44, v30
	s_mov_b64 s[20:21], s[0:1]
	s_nop 0
	v_addc_co_u32_e32 v7, vcc, 0, v31, vcc
	v_add_co_u32_e32 v10, vcc, s45, v30
	global_load_dwordx4 v[2:5], v[30:31], off nt
	s_nop 0
	global_load_dwordx4 v[6:9], v[6:7], off nt
	v_addc_co_u32_e32 v11, vcc, 0, v31, vcc
	v_add_co_u32_e32 v14, vcc, s46, v30
	v_mov_b32_e32 v41, v39
	s_nop 0
	v_addc_co_u32_e32 v15, vcc, 0, v31, vcc
	v_add_co_u32_e32 v18, vcc, s47, v30
	global_load_dwordx4 v[10:13], v[10:11], off nt
	s_nop 0
	global_load_dwordx4 v[14:17], v[14:15], off nt
	v_addc_co_u32_e32 v19, vcc, 0, v31, vcc
	v_add_co_u32_e32 v22, vcc, s48, v30
	v_or_b32_e32 v34, s23, v1
	s_nop 0
	v_addc_co_u32_e32 v23, vcc, 0, v31, vcc
	global_load_dwordx4 v[18:21], v[18:19], off nt
	s_nop 0
	global_load_dwordx4 v[22:25], v[22:23], off nt
	v_add_co_u32_e32 v26, vcc, s49, v30
	s_mov_b64 s[4:5], s[74:75]
	s_nop 0
	v_addc_co_u32_e32 v27, vcc, 0, v31, vcc
	global_load_dwordx4 v[26:29], v[26:27], off nt
	v_add_co_u32_e32 v30, vcc, s50, v30
	s_lshl_b64 s[20:21], s[6:7], 1
	s_nop 0
	v_addc_co_u32_e32 v31, vcc, 0, v31, vcc
	global_load_dwordx4 v[30:33], v[30:31], off nt
	s_waitcnt lgkmcnt(0)
	s_add_u32 s4, s4, s20
	s_addc_u32 s5, s5, s21
	v_lshl_add_u64 v[36:37], s[4:5], 0, v[40:41]
	v_mov_b32_e32 v35, v39
	v_lshlrev_b32_e32 v34, 10, v34
	v_lshl_add_u64 v[36:37], v[36:37], 0, s[16:17]
	s_waitcnt vmcnt(4)
	ds_write2_b32 v51, v2, v3 offset1:1
	ds_write2_b32 v51, v4, v5 offset0:2 offset1:3
	ds_write2_b32 v52, v6, v7 offset1:1
	ds_write2_b32 v53, v8, v9 offset1:1
	ds_write2_b32 v54, v10, v11 offset1:1
	ds_write2_b32 v55, v12, v13 offset1:1
	ds_write2_b32 v56, v14, v15 offset1:1
	ds_write2_b32 v57, v16, v17 offset1:1
	s_waitcnt vmcnt(3)
	ds_write2_b32 v58, v18, v19 offset1:1
	ds_write2_b32 v59, v20, v21 offset1:1
	s_waitcnt vmcnt(2)
	ds_write2_b32 v60, v22, v23 offset1:1
	ds_write2_b32 v61, v24, v25 offset1:1
	s_waitcnt vmcnt(1)
	ds_write2_b32 v62, v26, v27 offset1:1
	ds_write2_b32 v63, v28, v29 offset1:1
	s_waitcnt vmcnt(0)
	ds_write2_b32 v64, v30, v31 offset1:1
	ds_write2_b32 v65, v32, v33 offset1:1
	s_waitcnt lgkmcnt(0)
	ds_read2_b32 v[6:7], v49 offset0:33 offset1:41
	ds_read2_b32 v[8:9], v49 offset1:8
	ds_read2_b32 v[10:11], v49 offset0:66 offset1:74
	ds_read2_b32 v[12:13], v49 offset0:99 offset1:107
	ds_read2_b32 v[14:15], v49 offset0:132 offset1:140
	ds_read2_b32 v[16:17], v49 offset0:165 offset1:173
	ds_read2_b32 v[18:19], v49 offset0:198 offset1:206
	ds_read2_b32 v[20:21], v49 offset0:231 offset1:239
	v_lshl_add_u64 v[22:23], v[36:37], 0, v[34:35]
	s_waitcnt lgkmcnt(6)
	v_cvt_pk_bf16_f32 v2, v8, v6
	s_waitcnt lgkmcnt(4)
	v_cvt_pk_bf16_f32 v3, v10, v12
	s_waitcnt lgkmcnt(2)
	v_cvt_pk_bf16_f32 v4, v14, v16
	s_waitcnt lgkmcnt(0)
	v_cvt_pk_bf16_f32 v5, v18, v20
	global_store_dwordx4 v[22:23], v[2:5], off
	v_cvt_pk_bf16_f32 v6, v9, v7
	v_cvt_pk_bf16_f32 v7, v11, v13
	v_cvt_pk_bf16_f32 v8, v15, v17
	v_cvt_pk_bf16_f32 v9, v19, v21
	v_or_b32_e32 v2, s23, v46
	ds_read2_b32 v[10:11], v49 offset0:49 offset1:57
	ds_read2_b32 v[12:13], v49 offset0:16 offset1:24
	ds_read2_b32 v[14:15], v49 offset0:82 offset1:90
	ds_read2_b32 v[16:17], v49 offset0:115 offset1:123
	ds_read2_b32 v[18:19], v49 offset0:148 offset1:156
	ds_read2_b32 v[20:21], v49 offset0:181 offset1:189
	ds_read2_b32 v[22:23], v49 offset0:214 offset1:222
	ds_read2_b32 v[24:25], v49 offset0:247 offset1:255
	v_lshlrev_b32_e32 v2, 10, v2
	v_mov_b32_e32 v3, v39
	v_lshl_add_u64 v[2:3], v[36:37], 0, v[2:3]
	global_store_dwordx4 v[2:3], v[6:9], off
	s_waitcnt lgkmcnt(6)
	v_cvt_pk_bf16_f32 v2, v12, v10
	s_waitcnt lgkmcnt(4)
	v_cvt_pk_bf16_f32 v3, v14, v16
	v_or_b32_e32 v6, s23, v47
	v_lshlrev_b32_e32 v6, 10, v6
	v_mov_b32_e32 v7, v39
	s_waitcnt lgkmcnt(2)
	v_cvt_pk_bf16_f32 v4, v18, v20
	s_waitcnt lgkmcnt(0)
	v_cvt_pk_bf16_f32 v5, v22, v24
	v_lshl_add_u64 v[6:7], v[36:37], 0, v[6:7]
	global_store_dwordx4 v[6:7], v[2:5], off
	v_or_b32_e32 v6, s23, v48
	v_lshlrev_b32_e32 v6, 10, v6
	v_mov_b32_e32 v7, v39
	v_cvt_pk_bf16_f32 v2, v13, v11
	v_cvt_pk_bf16_f32 v3, v15, v17
	v_cvt_pk_bf16_f32 v4, v19, v21
	v_cvt_pk_bf16_f32 v5, v23, v25
	v_lshl_add_u64 v[6:7], v[36:37], 0, v[6:7]
	global_store_dwordx4 v[6:7], v[2:5], off
	s_waitcnt lgkmcnt(0)

; #define LAS __attribute__((address_space(3)))
; __device__ __forceinline__ unsigned cvtpk(float lo, float hi) { f32x2 v = {lo, hi}; bf16x2_t b = __builtin_convertvector(v, bf16x2_t); return __builtin_bit_cast(unsigned, b); }
; __device__ __forceinline__ void tr_item(const float* __restrict__ W, int ldw, int K, bf16* __restrict__ WT, int nblk, int mapmode, const float* __restrict__ ksc, LAS float* scr, int item, int lane) {
;     const int kb = item / nblk, nb = item - kb * nblk, k0 = 64 * kb, n0 = 32 * nb;
;     const int L = (n0 & ~255) + 64 * ((n0 >> 5) & 3) + 32 * ((n0 >> 7) & 1);
;     const int src0 = mapmode ? ((L >> 5) & 1) * DFF + 128 * (L >> 8) + 32 * ((L >> 6) & 3) : L;
;     f32x4 v[8];
; #pragma unroll
;     for (int i = 0; i < 8; ++i) { const int kk = 8 * i + (lane >> 3); v[i] = __builtin_nontemporal_load((const f32x4*)(W + (size_t)(k0 + kk) * ldw + src0 + 4 * (lane & 7))); }
; #pragma unroll
;     for (int i = 0; i < 8; ++i) { const int kk = 8 * i + (lane >> 3); f32x4 w = v[i]; if (ksc) w *= ksc[k0 + kk];
;         LAS float* d = scr + kk * 33 + 4 * (lane & 7); d[0] = w[0]; d[1] = w[1]; d[2] = w[2]; d[3] = w[3]; }
;     asm volatile("s_waitcnt lgkmcnt(0)" ::: "memory");
;     const int c = lane & 7;
; #pragma unroll
;     for (int j = 0; j < 4; ++j) { const int n = (lane >> 3) + 8 * j; const LAS float* s = scr + (8 * c) * 33 + n;
;         u32x4 o; o.x = cvtpk(s[0 * 33], s[1 * 33]); o.y = cvtpk(s[2 * 33], s[3 * 33]); o.z = cvtpk(s[4 * 33], s[5 * 33]); o.w = cvtpk(s[6 * 33], s[7 * 33]);
;         *(u32x4*)(WT + (size_t)(n0 + n) * K + k0 + 8 * c) = o; }
;     asm volatile("s_waitcnt lgkmcnt(0)" ::: "memory");
.LBB0_552:
	s_andn2_b64 vcc, exec, s[4:5]
	s_cbranch_vccnz .LBB0_517
	s_mov_b64 s[4:5], s[0:1]
	s_mov_b64 s[20:21], s[72:73]
	s_ashr_i32 s4, s28, 31
	s_lshr_b32 s4, s4, 28
	s_add_i32 s4, s28, s4
	s_ashr_i32 s5, s4, 4
	s_lshl_b32 s4, s5, 6
	s_lshl_b32 s6, s5, 9
	s_add_i32 s5, s30, s55
	s_sub_i32 s5, s5, s6
	s_and_b32 s24, s35, 0xc0
	s_and_b32 s25, s33, 32
	s_and_b32 s5, s5, 0xffffff00
	s_or_b32 s24, s24, s25
	s_or_b32 s24, s24, s5
	s_ashr_i32 s25, s24, 31
	v_or_b32_e32 v30, s4, v1
	s_lshl_b64 s[24:25], s[24:25], 2
	s_waitcnt lgkmcnt(0)
	s_add_u32 s20, s20, s24
	v_or_b32_e32 v4, 8, v30
	v_or_b32_e32 v10, 16, v30
	v_or_b32_e32 v12, 24, v30
	v_or_b32_e32 v18, 32, v30
	v_or_b32_e32 v20, 40, v30
	s_addc_u32 s21, s21, s25
	v_ashrrev_i32_e32 v31, 31, v30
	v_ashrrev_i32_e32 v5, 31, v4
	v_ashrrev_i32_e32 v11, 31, v10
	v_ashrrev_i32_e32 v13, 31, v12
	v_ashrrev_i32_e32 v19, 31, v18
	v_ashrrev_i32_e32 v21, 31, v20
	v_lshl_add_u64 v[32:33], s[20:21], 0, v[38:39]
	v_lshlrev_b64 v[2:3], 11, v[30:31]
	v_lshlrev_b64 v[4:5], 11, v[4:5]
	v_lshlrev_b64 v[10:11], 11, v[10:11]
	v_lshlrev_b64 v[12:13], 11, v[12:13]
	v_lshlrev_b64 v[18:19], 11, v[18:19]
	v_lshlrev_b64 v[20:21], 11, v[20:21]
	s_mov_b64 s[22:23], s[0:1]
	v_lshl_add_u64 v[2:3], v[32:33], 0, v[2:3]
	v_lshl_add_u64 v[6:7], v[32:33], 0, v[4:5]
	v_lshl_add_u64 v[10:11], v[32:33], 0, v[10:11]
	v_lshl_add_u64 v[14:15], v[32:33], 0, v[12:13]
	v_lshl_add_u64 v[18:19], v[32:33], 0, v[18:19]
	s_waitcnt vmcnt(0)
	v_lshl_add_u64 v[22:23], v[32:33], 0, v[20:21]
	global_load_dwordx4 v[2:5], v[2:3], off nt
	s_nop 0
	global_load_dwordx4 v[6:9], v[6:7], off nt
	s_nop 0
	global_load_dwordx4 v[10:13], v[10:11], off nt
	s_nop 0
	global_load_dwordx4 v[14:17], v[14:15], off nt
	s_nop 0
	global_load_dwordx4 v[18:21], v[18:19], off nt
	s_nop 0
	global_load_dwordx4 v[22:25], v[22:23], off nt
	v_or_b32_e32 v26, 48, v30
	v_ashrrev_i32_e32 v27, 31, v26
	v_lshlrev_b64 v[26:27], 11, v[26:27]
	v_or_b32_e32 v30, 56, v30
	v_lshl_add_u64 v[26:27], v[32:33], 0, v[26:27]
	v_ashrrev_i32_e32 v31, 31, v30
	global_load_dwordx4 v[26:29], v[26:27], off nt
	v_lshlrev_b64 v[30:31], 11, v[30:31]
	v_lshl_add_u64 v[30:31], v[32:33], 0, v[30:31]
	global_load_dwordx4 v[30:33], v[30:31], off nt
	s_mov_b64 s[20:21], s[74:75]
	s_ashr_i32 s5, s4, 31
	s_lshl_b64 s[4:5], s[4:5], 1
	v_mov_b32_e32 v41, v39
	s_waitcnt vmcnt(7)
	ds_write2_b32 v51, v2, v3 offset1:1
	ds_write2_b32 v51, v4, v5 offset0:2 offset1:3
	s_waitcnt vmcnt(6)
	ds_write2_b32 v52, v6, v7 offset1:1
	ds_write2_b32 v53, v8, v9 offset1:1
	s_waitcnt vmcnt(5)
	ds_write2_b32 v54, v10, v11 offset1:1
	ds_write2_b32 v55, v12, v13 offset1:1
	s_waitcnt vmcnt(4)
	ds_write2_b32 v56, v14, v15 offset1:1
	ds_write2_b32 v57, v16, v17 offset1:1
	s_waitcnt vmcnt(3)
	ds_write2_b32 v58, v18, v19 offset1:1
	ds_write2_b32 v59, v20, v21 offset1:1
	s_waitcnt vmcnt(2)
	ds_write2_b32 v60, v22, v23 offset1:1
	ds_write2_b32 v61, v24, v25 offset1:1
	s_waitcnt vmcnt(1)
	ds_write2_b32 v62, v26, v27 offset1:1
	ds_write2_b32 v63, v28, v29 offset1:1
	s_waitcnt vmcnt(0)
	ds_write2_b32 v64, v30, v31 offset1:1
	ds_write2_b32 v65, v32, v33 offset1:1
	s_waitcnt lgkmcnt(0)
	s_waitcnt lgkmcnt(0)
	s_add_u32 s4, s20, s4
	ds_read2_b32 v[6:7], v49 offset0:33 offset1:41
	ds_read2_b32 v[8:9], v49 offset1:8
	ds_read2_b32 v[10:11], v49 offset0:66 offset1:74
	ds_read2_b32 v[12:13], v49 offset0:99 offset1:107
	ds_read2_b32 v[14:15], v49 offset0:132 offset1:140
	ds_read2_b32 v[16:17], v49 offset0:165 offset1:173
	ds_read2_b32 v[18:19], v49 offset0:198 offset1:206
	ds_read2_b32 v[20:21], v49 offset0:231 offset1:239
	s_addc_u32 s5, s21, s5
	s_sub_i32 s6, s55, s6
	v_add_u32_e32 v36, s6, v50
	v_lshl_add_u64 v[34:35], s[4:5], 0, v[40:41]
	v_ashrrev_i32_e32 v37, 31, v36
	v_lshl_add_u64 v[22:23], v[34:35], 0, s[18:19]
	v_lshlrev_b64 v[24:25], 10, v[36:37]
	s_waitcnt lgkmcnt(6)
	v_cvt_pk_bf16_f32 v2, v8, v6
	s_waitcnt lgkmcnt(4)
	v_cvt_pk_bf16_f32 v3, v10, v12
	s_waitcnt lgkmcnt(2)
	v_cvt_pk_bf16_f32 v4, v14, v16
	s_waitcnt lgkmcnt(0)
	v_cvt_pk_bf16_f32 v5, v18, v20
	v_lshl_add_u64 v[24:25], v[22:23], 0, v[24:25]
	v_add_u32_e32 v6, 8, v36
	global_store_dwordx4 v[24:25], v[2:5], off
	s_nop 1
	v_cvt_pk_bf16_f32 v2, v9, v7
	v_ashrrev_i32_e32 v7, 31, v6
	v_cvt_pk_bf16_f32 v3, v11, v13
	v_cvt_pk_bf16_f32 v4, v15, v17
	v_cvt_pk_bf16_f32 v5, v19, v21
	v_lshlrev_b64 v[6:7], 10, v[6:7]
	ds_read2_b32 v[8:9], v49 offset0:49 offset1:57
	ds_read2_b32 v[10:11], v49 offset0:16 offset1:24
	ds_read2_b32 v[12:13], v49 offset0:82 offset1:90
	ds_read2_b32 v[14:15], v49 offset0:115 offset1:123
	ds_read2_b32 v[16:17], v49 offset0:148 offset1:156
	ds_read2_b32 v[18:19], v49 offset0:181 offset1:189
	ds_read2_b32 v[20:21], v49 offset0:214 offset1:222
	ds_read2_b32 v[24:25], v49 offset0:247 offset1:255
	v_lshl_add_u64 v[6:7], v[22:23], 0, v[6:7]
	global_store_dwordx4 v[6:7], v[2:5], off
	v_add_u32_e32 v6, 16, v36
	v_ashrrev_i32_e32 v7, 31, v6
	v_lshlrev_b64 v[6:7], 10, v[6:7]
	s_waitcnt lgkmcnt(6)
	v_cvt_pk_bf16_f32 v2, v10, v8
	s_waitcnt lgkmcnt(4)
	v_cvt_pk_bf16_f32 v3, v12, v14
	s_waitcnt lgkmcnt(2)
	v_cvt_pk_bf16_f32 v4, v16, v18
	s_waitcnt lgkmcnt(0)
	v_cvt_pk_bf16_f32 v5, v20, v24
	v_lshl_add_u64 v[6:7], v[22:23], 0, v[6:7]
	global_store_dwordx4 v[6:7], v[2:5], off
	v_add_u32_e32 v6, 24, v36
	v_ashrrev_i32_e32 v7, 31, v6
	v_lshlrev_b64 v[6:7], 10, v[6:7]
	v_cvt_pk_bf16_f32 v2, v11, v9
	v_cvt_pk_bf16_f32 v3, v13, v15
	v_cvt_pk_bf16_f32 v4, v17, v19
	v_cvt_pk_bf16_f32 v5, v21, v25
	v_lshl_add_u64 v[6:7], v[22:23], 0, v[6:7]
	global_store_dwordx4 v[6:7], v[2:5], off
	s_waitcnt lgkmcnt(0)
	s_branch .LBB0_517
